# XCD-local FF1-to-FF2 seam now guarded by a run-time placement check (each blockIdx%8 group must sit on one XCD, verified through 8 OR-ed words after the first grid barrier; otherwise that seam stays a
# speedup vs baseline: 1.0118x; 1.0118x over previous
_Z6mk_fwd4Args:
	s_load_dword s33, s[0:1], 0xc0
	s_add_u32 s4, s0, 0xc0
	s_addc_u32 s5, s1, 0
	v_readfirstlane_b32 s10, v0
	s_mov_b32 s100, 0
	s_mov_b32 s101, 0
	v_writelane_b32 v252, s4, 0
	s_nop 1
	v_writelane_b32 v252, s5, 1
	s_waitcnt lgkmcnt(0)
	s_and_b32 s4, s33, 7
	s_cmp_lg_u32 s4, 0
	v_writelane_b32 v252, s2, 2
	s_cbranch_scc1 .LBB0_2
	s_ashr_i32 s5, s2, 31
	s_lshr_b32 s5, s5, 29
	s_add_i32 s5, s2, s5
	s_and_b32 s6, s5, -8
	s_ashr_i32 s4, s33, 3
	s_sub_i32 s6, s2, s6
	s_mul_i32 s4, s4, s6
	s_ashr_i32 s5, s5, 3
	s_add_i32 s4, s4, s5
	v_writelane_b32 v252, s4, 2

.LBB0_5:
	v_add_u32_e32 v1, 0x200, v1
	v_cmp_lt_u32_e32 vcc, s8, v1
	ds_write_b128 v6, v[2:5]
	s_or_b64 s[4:5], vcc, s[4:5]
	v_add_u32_e32 v6, 0x2000, v6
	s_andn2_b64 exec, exec, s[4:5]
	s_cbranch_execnz .LBB0_5
	s_or_b64 exec, exec, s[4:5]
	s_waitcnt lgkmcnt(0)
	s_barrier
	s_add_u32 s76, s46, 0x4000
	s_getreg_b32 s4, hwreg(HW_REG_XCC_ID, 0, 4)
	s_addc_u32 s77, s47, 0
	s_and_b32 s75, s4, 15
	v_cmp_eq_u32_e64 s[52:53], 0, v0
	s_and_saveexec_b64 s[4:5], s[52:53]
	s_cbranch_execz .LBB0_9
	s_mov_b64 s[8:9], exec
	v_mbcnt_lo_u32_b32 v1, s8, 0
	v_mbcnt_hi_u32_b32 v1, s9, v1
	v_cmp_eq_u32_e32 vcc, 0, v1
	s_and_b64 s[12:13], exec, vcc
	s_mov_b64 exec, s[12:13]
	s_cbranch_execz .LBB0_9
	s_lshl_b32 s11, s75, 8
	s_bcnt1_i32_b64 s8, s[8:9]
	v_mov_b32_e32 v1, s11
	v_mov_b32_e32 v2, s8
	global_atomic_add v1, v2, s[76:77] offset:1024
	s_and_b32 s11, s2, 7
	s_lshl_b32 s11, s11, 2
	s_add_i32 s11, s11, 0x20000
	s_lshl_b32 s8, 1, s75
	v_mov_b32_e32 v238, s11
	v_mov_b32_e32 v239, s8
	global_atomic_or v238, v239, s[46:47]

.LBB0_204:
	s_or_b64 exec, exec, s[4:5]
	s_waitcnt lgkmcnt(0)
	s_barrier
	s_mov_b32 s100, 0
	v_mov_b32_e32 v238, 0x20000
	global_load_dwordx4 v[240:243], v238, s[46:47] sc1
	global_load_dwordx4 v[244:247], v238, s[46:47] offset:16 sc1
	s_waitcnt vmcnt(0)
	v_bcnt_u32_b32 v240, v240, 0
	v_bcnt_u32_b32 v241, v241, 0
	v_bcnt_u32_b32 v242, v242, 0
	v_bcnt_u32_b32 v243, v243, 0
	v_bcnt_u32_b32 v244, v244, 0
	v_bcnt_u32_b32 v245, v245, 0
	v_bcnt_u32_b32 v246, v246, 0
	v_bcnt_u32_b32 v247, v247, 0
	v_max3_u32 v238, v240, v241, v242
	v_max3_u32 v238, v238, v243, v244
	v_max3_u32 v238, v238, v245, v246
	v_max_u32_e32 v238, v238, v247
	v_min3_u32 v239, v240, v241, v242
	v_min3_u32 v239, v239, v243, v244
	v_min3_u32 v239, v239, v245, v246
	v_min_u32_e32 v239, v239, v247
	v_sub_u32_e32 v239, v238, v239
	v_xor_b32_e32 v238, 1, v238
	v_or_b32_e32 v238, v238, v239
	s_nop 0
	v_readfirstlane_b32 s101, v238
	s_cmp_eq_u32 s101, 0
	s_cselect_b32 s101, 1, 0

.LBB0_1061:
	s_andn2_saveexec_b64 s[4:5], s[10:11]
	s_cbranch_execz .LBB0_1081
	s_mov_b64 s[10:11], exec
	s_cmp_eq_u32 s101, 1
	s_cbranch_scc0 .Lmy_xl_glob
	buffer_inv sc1
	s_branch .Lmy_xl_rel
.Lmy_xl_glob:
	buffer_wbl2 sc1
	buffer_inv sc1
	s_waitcnt lgkmcnt(0)
	s_waitcnt vmcnt(0)
	v_mbcnt_lo_u32_b32 v3, s10, 0
	v_mbcnt_hi_u32_b32 v3, s11, v3
	v_cmp_eq_u32_e32 vcc, 0, v3
	s_and_saveexec_b64 s[14:15], vcc
	s_cbranch_execz .LBB0_1064
	s_bcnt1_i32_b64 s4, s[10:11]
	v_mov_b32_e32 v4, s4
	v_readlane_b32 s4, v253, 42
	v_readlane_b32 s5, v253, 43
	s_nop 4
	global_atomic_add v4, v99, v4, s[4:5] sc0
